# norm row loops (NORM1, NORM2W): the four x quads and twelve gamma/scale/shift quads of a row loaded together at the top of the row; sections run without vmcnt waits
# speedup vs baseline: 1.0033x; 1.0018x over previous
.LBB0_1183:
	global_load_dwordx4 v[12:15], v21, s[8:9]
	global_load_dwordx4 v[8:11], v21, s[8:9] offset:1024
	global_load_dwordx4 v[4:7], v21, s[8:9] offset:2048
	global_load_dwordx4 v[40:43], v21, s[8:9] offset:3072
	s_lshl_b64 s[6:7], s[6:7], 2
	s_add_u32 s6, s12, s6
	s_addc_u32 s7, s13, s7
	s_add_u32 s8, s6, 0x1000
	s_addc_u32 s9, s7, 0
	global_load_dwordx4 v[44:47], v[16:17], off
	global_load_dwordx4 v[60:63], v21, s[8:9]
	global_load_dwordx4 v[76:79], v21, s[6:7]
	global_load_dwordx4 v[48:51], v[16:17], off offset:1024
	global_load_dwordx4 v[64:67], v22, s[8:9]
	global_load_dwordx4 v[80:83], v21, s[6:7] offset:1024
	global_load_dwordx4 v[52:55], v[16:17], off offset:2048
	global_load_dwordx4 v[68:71], v23, s[8:9]
	global_load_dwordx4 v[84:87], v21, s[6:7] offset:2048
	global_load_dwordx4 v[56:59], v[16:17], off offset:3072
	global_load_dwordx4 v[72:75], v24, s[8:9]
	global_load_dwordx4 v[88:91], v21, s[6:7] offset:3072
	s_waitcnt vmcnt(13)
	v_mul_f32_e32 v0, v13, v13
	v_mul_f32_e32 v1, v15, v15
	v_fmac_f32_e32 v0, v12, v12
	v_fmac_f32_e32 v1, v14, v14
	v_add_f32_e32 v0, v0, v1
	v_mul_f32_e32 v1, v9, v9
	v_mul_f32_e32 v2, v11, v11
	v_fmac_f32_e32 v1, v8, v8
	v_fmac_f32_e32 v2, v10, v10
	v_add_f32_e32 v1, v1, v2
	v_add_f32_e32 v0, v0, v1
	v_mul_f32_e32 v1, v5, v5
	v_mul_f32_e32 v2, v7, v7
	v_fmac_f32_e32 v1, v4, v4
	v_fmac_f32_e32 v2, v6, v6
	v_add_f32_e32 v1, v1, v2
	v_add_f32_e32 v20, v0, v1
	s_lshl_b64 s[10:11], s[10:11], 11
	s_waitcnt vmcnt(12)
	v_mul_f32_e32 v25, v41, v41
	v_mul_f32_e32 v26, v43, v43
	v_fmac_f32_e32 v25, v40, v40
	v_fmac_f32_e32 v26, v42, v42
	v_add_f32_e32 v25, v25, v26
	v_add_f32_e32 v20, v20, v25
	s_nop 1
	v_add_f32_dpp v20, v20, v20 quad_perm:[1,0,3,2] row_mask:0xf bank_mask:0xf bound_ctrl:1
	s_nop 1
	v_add_f32_dpp v20, v20, v20 quad_perm:[2,3,0,1] row_mask:0xf bank_mask:0xf bound_ctrl:1
	s_nop 1
	v_add_f32_dpp v20, v20, v20 row_half_mirror row_mask:0xf bank_mask:0xf bound_ctrl:1
	s_nop 1
	v_add_f32_dpp v20, v20, v20 row_mirror row_mask:0xf bank_mask:0xf bound_ctrl:1
	v_mov_b32_e32 v25, v20
	s_nop 1
	v_permlane16_swap_b32 v20, v25
	s_nop 1
	s_nop 0
	v_add_f32_e32 v20, v20, v25
	v_mov_b32_e32 v25, v20
	s_nop 1
	v_permlane32_swap_b32 v20, v25
	s_nop 1
	v_add_f32_e32 v20, v20, v25
	v_fmamk_f32 v20, v20, 0x3a800000, v226
	v_cmp_gt_f32_e32 vcc, s82, v20
	v_mul_f32_e32 v25, 0x4b800000, v20
	s_nop 0
	v_cndmask_b32_e32 v20, v20, v25, vcc
	v_rsq_f32_e32 v20, v20
	s_nop 0
	v_mul_f32_e32 v25, 0x45800000, v20
	v_cndmask_b32_e32 v20, v20, v25, vcc
	v_pk_mul_f32 v[14:15], v[14:15], v[20:21] op_sel_hi:[1,0]
	v_pk_mul_f32 v[12:13], v[12:13], v[20:21] op_sel_hi:[1,0]
	v_pk_mul_f32 v[10:11], v[10:11], v[20:21] op_sel_hi:[1,0]
	v_pk_mul_f32 v[8:9], v[8:9], v[20:21] op_sel_hi:[1,0]
	v_pk_mul_f32 v[6:7], v[6:7], v[20:21] op_sel_hi:[1,0]
	v_pk_mul_f32 v[4:5], v[4:5], v[20:21] op_sel_hi:[1,0]
	v_pk_mul_f32 v[2:3], v[42:43], v[20:21] op_sel_hi:[1,0]
	v_pk_mul_f32 v[0:1], v[40:41], v[20:21] op_sel_hi:[1,0]
	s_waitcnt vmcnt(0)
	v_pk_mul_f32 v[12:13], v[44:45], v[12:13]
	v_pk_mul_f32 v[14:15], v[46:47], v[14:15]
	v_pk_add_f32 v[28:29], v[60:61], 1.0 op_sel_hi:[1,0]
	v_pk_add_f32 v[26:27], v[62:63], 1.0 op_sel_hi:[1,0]
	v_pk_fma_f32 v[12:13], v[28:29], v[12:13], v[76:77]
	v_lshl_add_u64 v[34:35], v[18:19], 0, s[10:11]
	v_pk_fma_f32 v[14:15], v[26:27], v[14:15], v[78:79]
	v_cvt_pk_bf16_f32 v12, v12, v13
	s_nop 0
	v_cvt_pk_bf16_f32 v13, v14, v15
	global_store_dwordx2 v[34:35], v[12:13], off
	s_nop 0
	v_pk_mul_f32 v[8:9], v[48:49], v[8:9]
	v_pk_mul_f32 v[10:11], v[50:51], v[10:11]
	v_pk_add_f32 v[14:15], v[64:65], 1.0 op_sel_hi:[1,0]
	v_pk_add_f32 v[12:13], v[66:67], 1.0 op_sel_hi:[1,0]
	v_pk_fma_f32 v[8:9], v[14:15], v[8:9], v[80:81]
	v_pk_fma_f32 v[10:11], v[12:13], v[10:11], v[82:83]
	v_cvt_pk_bf16_f32 v8, v8, v9
	s_nop 0
	v_cvt_pk_bf16_f32 v9, v10, v11
	global_store_dwordx2 v[34:35], v[8:9], off offset:512
	s_nop 0
	v_pk_mul_f32 v[4:5], v[4:5], v[52:53]
	v_pk_mul_f32 v[6:7], v[6:7], v[54:55]
	v_pk_add_f32 v[10:11], v[68:69], 1.0 op_sel_hi:[1,0]
	v_pk_add_f32 v[8:9], v[70:71], 1.0 op_sel_hi:[1,0]
	v_pk_fma_f32 v[4:5], v[4:5], v[10:11], v[84:85]
	v_pk_fma_f32 v[6:7], v[6:7], v[8:9], v[86:87]
	v_cvt_pk_bf16_f32 v4, v4, v5
	s_nop 0
	v_cvt_pk_bf16_f32 v5, v6, v7
	global_store_dwordx2 v[34:35], v[4:5], off offset:1024
	s_nop 0
	v_readlane_b32 s6, v254, 22
	v_readlane_b32 s7, v254, 23
	s_add_u32 s4, s4, s6
	s_addc_u32 s5, s5, s7
	s_add_u32 s0, s0, s2
	s_addc_u32 s1, s1, s3
	s_cmpk_lt_i32 s4, 0x4200
	v_pk_mul_f32 v[0:1], v[0:1], v[56:57]
	v_pk_mul_f32 v[2:3], v[2:3], v[58:59]
	v_pk_add_f32 v[6:7], v[72:73], 1.0 op_sel_hi:[1,0]
	v_pk_add_f32 v[4:5], v[74:75], 1.0 op_sel_hi:[1,0]
	v_pk_fma_f32 v[0:1], v[0:1], v[6:7], v[88:89]
	v_pk_fma_f32 v[2:3], v[2:3], v[4:5], v[90:91]
	v_cvt_pk_bf16_f32 v0, v0, v1
	s_nop 0
	v_cvt_pk_bf16_f32 v1, v2, v3
	global_store_dwordx2 v[34:35], v[0:1], off offset:1536
	s_cbranch_scc0 .LBB0_1188

.LBB0_1298:
	global_load_dwordx4 v[12:15], v21, s[8:9]
	global_load_dwordx4 v[8:11], v21, s[8:9] offset:1024
	global_load_dwordx4 v[4:7], v21, s[8:9] offset:2048
	global_load_dwordx4 v[40:43], v21, s[8:9] offset:3072
	s_lshl_b64 s[6:7], s[6:7], 2
	s_add_u32 s6, s14, s6
	s_addc_u32 s7, s15, s7
	s_add_u32 s8, s6, 0x1000
	s_addc_u32 s9, s7, 0
	global_load_dwordx4 v[44:47], v[16:17], off
	global_load_dwordx4 v[60:63], v21, s[8:9]
	global_load_dwordx4 v[76:79], v21, s[6:7]
	global_load_dwordx4 v[48:51], v[16:17], off offset:1024
	global_load_dwordx4 v[64:67], v22, s[8:9]
	global_load_dwordx4 v[80:83], v21, s[6:7] offset:1024
	global_load_dwordx4 v[52:55], v[16:17], off offset:2048
	global_load_dwordx4 v[68:71], v23, s[8:9]
	global_load_dwordx4 v[84:87], v21, s[6:7] offset:2048
	global_load_dwordx4 v[56:59], v[16:17], off offset:3072
	global_load_dwordx4 v[72:75], v24, s[8:9]
	global_load_dwordx4 v[88:91], v21, s[6:7] offset:3072
	s_waitcnt vmcnt(15)
	v_mul_f32_e32 v0, v13, v13
	v_mul_f32_e32 v1, v15, v15
	v_fmac_f32_e32 v0, v12, v12
	v_fmac_f32_e32 v1, v14, v14
	v_add_f32_e32 v0, v0, v1
	s_waitcnt vmcnt(14)
	v_mul_f32_e32 v1, v9, v9
	v_mul_f32_e32 v2, v11, v11
	v_fmac_f32_e32 v1, v8, v8
	v_fmac_f32_e32 v2, v10, v10
	v_add_f32_e32 v1, v1, v2
	v_add_f32_e32 v0, v0, v1
	s_waitcnt vmcnt(13)
	v_mul_f32_e32 v1, v5, v5
	v_mul_f32_e32 v2, v7, v7
	v_fmac_f32_e32 v1, v4, v4
	v_fmac_f32_e32 v2, v6, v6
	v_add_f32_e32 v1, v1, v2
	v_add_f32_e32 v20, v0, v1
	s_lshl_b64 s[10:11], s[10:11], 11
	s_waitcnt vmcnt(12)
	v_mul_f32_e32 v25, v41, v41
	v_mul_f32_e32 v26, v43, v43
	v_fmac_f32_e32 v25, v40, v40
	v_fmac_f32_e32 v26, v42, v42
	v_add_f32_e32 v25, v25, v26
	v_add_f32_e32 v20, v20, v25
	s_nop 1
	v_add_f32_dpp v20, v20, v20 quad_perm:[1,0,3,2] row_mask:0xf bank_mask:0xf bound_ctrl:1
	s_nop 1
	v_add_f32_dpp v20, v20, v20 quad_perm:[2,3,0,1] row_mask:0xf bank_mask:0xf bound_ctrl:1
	s_nop 1
	v_add_f32_dpp v20, v20, v20 row_half_mirror row_mask:0xf bank_mask:0xf bound_ctrl:1
	s_nop 1
	v_add_f32_dpp v20, v20, v20 row_mirror row_mask:0xf bank_mask:0xf bound_ctrl:1
	v_mov_b32_e32 v25, v20
	s_nop 1
	v_permlane16_swap_b32 v20, v25
	s_nop 1
	s_nop 0
	v_add_f32_e32 v20, v20, v25
	v_mov_b32_e32 v25, v20
	s_nop 1
	v_permlane32_swap_b32 v20, v25
	s_nop 1
	v_add_f32_e32 v20, v20, v25
	v_fmamk_f32 v20, v20, 0x3a800000, v226
	v_cmp_gt_f32_e32 vcc, s82, v20
	v_mul_f32_e32 v25, 0x4b800000, v20
	s_nop 0
	v_cndmask_b32_e32 v20, v20, v25, vcc
	v_rsq_f32_e32 v20, v20
	s_nop 0
	v_mul_f32_e32 v25, 0x45800000, v20
	v_cndmask_b32_e32 v20, v20, v25, vcc
	v_pk_mul_f32 v[14:15], v[14:15], v[20:21] op_sel_hi:[1,0]
	v_pk_mul_f32 v[12:13], v[12:13], v[20:21] op_sel_hi:[1,0]
	v_pk_mul_f32 v[10:11], v[10:11], v[20:21] op_sel_hi:[1,0]
	v_pk_mul_f32 v[8:9], v[8:9], v[20:21] op_sel_hi:[1,0]
	v_pk_mul_f32 v[6:7], v[6:7], v[20:21] op_sel_hi:[1,0]
	v_pk_mul_f32 v[4:5], v[4:5], v[20:21] op_sel_hi:[1,0]
	v_pk_mul_f32 v[2:3], v[42:43], v[20:21] op_sel_hi:[1,0]
	v_pk_mul_f32 v[0:1], v[40:41], v[20:21] op_sel_hi:[1,0]
	s_waitcnt vmcnt(0)
	v_pk_mul_f32 v[12:13], v[44:45], v[12:13]
	v_pk_mul_f32 v[14:15], v[46:47], v[14:15]
	v_pk_add_f32 v[28:29], v[60:61], 1.0 op_sel_hi:[1,0]
	v_pk_add_f32 v[26:27], v[62:63], 1.0 op_sel_hi:[1,0]
	v_pk_fma_f32 v[12:13], v[28:29], v[12:13], v[76:77]
	v_lshl_add_u64 v[34:35], v[18:19], 0, s[10:11]
	v_pk_fma_f32 v[14:15], v[26:27], v[14:15], v[78:79]
	v_cvt_pk_bf16_f32 v12, v12, v13
	s_nop 0
	v_cvt_pk_bf16_f32 v13, v14, v15
	global_store_dwordx2 v[34:35], v[12:13], off
	s_nop 0
	v_pk_mul_f32 v[8:9], v[48:49], v[8:9]
	v_pk_mul_f32 v[10:11], v[50:51], v[10:11]
	v_pk_add_f32 v[14:15], v[64:65], 1.0 op_sel_hi:[1,0]
	v_pk_add_f32 v[12:13], v[66:67], 1.0 op_sel_hi:[1,0]
	v_pk_fma_f32 v[8:9], v[14:15], v[8:9], v[80:81]
	v_pk_fma_f32 v[10:11], v[12:13], v[10:11], v[82:83]
	v_cvt_pk_bf16_f32 v8, v8, v9
	s_nop 0
	v_cvt_pk_bf16_f32 v9, v10, v11
	global_store_dwordx2 v[34:35], v[8:9], off offset:512
	s_nop 0
	v_pk_mul_f32 v[4:5], v[4:5], v[52:53]
	v_pk_mul_f32 v[6:7], v[6:7], v[54:55]
	v_pk_add_f32 v[10:11], v[68:69], 1.0 op_sel_hi:[1,0]
	v_pk_add_f32 v[8:9], v[70:71], 1.0 op_sel_hi:[1,0]
	v_pk_fma_f32 v[4:5], v[4:5], v[10:11], v[84:85]
	v_pk_fma_f32 v[6:7], v[6:7], v[8:9], v[86:87]
	v_cvt_pk_bf16_f32 v4, v4, v5
	s_nop 0
	v_cvt_pk_bf16_f32 v5, v6, v7
	global_store_dwordx2 v[34:35], v[4:5], off offset:1024
	s_nop 0
	v_readlane_b32 s6, v254, 22
	v_readlane_b32 s7, v254, 23
	s_add_u32 s4, s4, s6
	s_addc_u32 s5, s5, s7
	s_add_u32 s0, s0, s2
	s_addc_u32 s1, s1, s3
	s_cmpk_gt_i32 s4, 0x41ff
	v_pk_mul_f32 v[0:1], v[0:1], v[56:57]
	v_pk_mul_f32 v[2:3], v[2:3], v[58:59]
	v_pk_add_f32 v[6:7], v[72:73], 1.0 op_sel_hi:[1,0]
	v_pk_add_f32 v[4:5], v[74:75], 1.0 op_sel_hi:[1,0]
	v_pk_fma_f32 v[0:1], v[0:1], v[6:7], v[88:89]
	v_pk_fma_f32 v[2:3], v[2:3], v[4:5], v[90:91]
	v_cvt_pk_bf16_f32 v0, v0, v1
	s_nop 0
	v_cvt_pk_bf16_f32 v1, v2, v3
	global_store_dwordx2 v[34:35], v[0:1], off offset:1536
	s_cbranch_scc1 .LBB0_1310
